# baseline (speedup 1.0000x reference)
; __device__ __forceinline__ float exp2_(float x) { return __builtin_amdgcn_exp2f(x); }
; __device__ __forceinline__ float log2_(float x) { return __builtin_amdgcn_logf(x); }
; __device__ __forceinline__ float rcp_(float x) { return __builtin_amdgcn_rcpf(x); }
; __device__ __forceinline__ float lo2f(unsigned u) { return __uint_as_float(u << 16); }
; __device__ __forceinline__ float hi2f(unsigned u) { return __uint_as_float(u & 0xffff0000u); }
; __device__ __forceinline__ void hgrn_block(const Params& p, int bh, char* smem) {
;     ...
;       float run[2] = {0.f, 0.f};
; #pragma unroll
;       for (int r = 0; r < 8; ++r) {
;         vv[r] = rv[r];
;         qv[r][0] = lo2f(rq[r]); qv[r][1] = hi2f(rq[r]);
;         float fl[2] = {lo2f(rf[r]), hi2f(rf[r])};
; #pragma unroll
;         for (int e = 0; e < 2; ++e) {
;           float sg = rcp_(1.f + exp2_(-1.4426950408889634f * fl[e]));
;           float k_ = (1.f - lb[e]) * (1.f - sg);
;           kv[r][e] = k_;
;           run[e] += log2_(1.f - k_);
;           gc[r][e] = run[e];
;         }
;       }
;       gsum[wid * 128 + d0] = run[0];
;       gsum[wid * 128 + d0 + 1] = run[1];
;       if (c + 1 < 32) {
; #pragma unroll
;         for (int r = 0; r < 8; ++r) {
;           const u16* zr = p.Z + (tokb + 64 + wid * 8 + r) * LDZ1 + h * 128 + d0;
;           rq[r] = *(const unsigned*)zr; rf[r] = *(const unsigned*)(zr + 2048); rv[r] = *(const unsigned*)(zr + 4096);
;         }
;       }
.LBB0_599:
	v_lshlrev_b32_e32 v32, 16, v111
	v_and_b32_e32 v33, 0xffff0000, v111
	v_mul_f32_e32 v32, 0xbfb8aa3b, v32
	v_mul_f32_e32 v33, 0xbfb8aa3b, v33
	v_exp_f32_e32 v32, v32
	v_exp_f32_e32 v33, v33
	v_lshlrev_b32_e32 v34, 16, v112
	s_cmp_eq_u32 s77, 1
	v_add_f32_e32 v32, 1.0, v32
	v_add_f32_e32 v33, 1.0, v33
	v_rcp_f32_e32 v32, v32
	v_rcp_f32_e32 v33, v33
	s_nop 0
	v_pk_add_f32 v[32:33], v[32:33], 1.0 op_sel_hi:[1,0] neg_lo:[1,0] neg_hi:[1,0]
	s_nop 0
	v_pk_mul_f32 v[90:91], v[56:57], v[32:33]
	v_and_b32_e32 v32, 0xffff0000, v112
	v_mul_f32_e32 v33, 0xbfb8aa3b, v34
	v_mul_f32_e32 v32, 0xbfb8aa3b, v32
	v_exp_f32_e32 v33, v33
	v_exp_f32_e32 v34, v32
	v_sub_f32_e32 v35, 1.0, v90
	v_add_f32_e32 v32, 1.0, v33
	v_add_f32_e32 v33, 1.0, v34
	v_rcp_f32_e32 v32, v32
	v_rcp_f32_e32 v33, v33
	v_log_f32_e32 v34, v35
	v_sub_f32_e32 v35, 1.0, v91
	v_log_f32_e32 v35, v35
	v_pk_add_f32 v[32:33], v[32:33], 1.0 op_sel_hi:[1,0] neg_lo:[1,0] neg_hi:[1,0]
	v_pk_add_f32 v[104:105], v[34:35], 0 op_sel_hi:[1,0]
	v_pk_mul_f32 v[86:87], v[56:57], v[32:33]
	v_lshlrev_b32_e32 v32, 16, v115
	v_and_b32_e32 v33, 0xffff0000, v115
	v_mul_f32_e32 v32, 0xbfb8aa3b, v32
	v_mul_f32_e32 v33, 0xbfb8aa3b, v33
	v_exp_f32_e32 v32, v32
	v_exp_f32_e32 v33, v33
	v_sub_f32_e32 v36, 1.0, v86
	v_sub_f32_e32 v37, 1.0, v87
	v_add_f32_e32 v32, 1.0, v32
	v_add_f32_e32 v33, 1.0, v33
	v_rcp_f32_e32 v32, v32
	v_rcp_f32_e32 v33, v33
	v_log_f32_e32 v36, v36
	v_log_f32_e32 v37, v37
	v_pk_add_f32 v[32:33], v[32:33], 1.0 op_sel_hi:[1,0] neg_lo:[1,0] neg_hi:[1,0]
	s_nop 0
	v_pk_mul_f32 v[84:85], v[56:57], v[32:33]
	v_lshlrev_b32_e32 v32, 16, v119
	v_and_b32_e32 v33, 0xffff0000, v119
	v_mul_f32_e32 v32, 0xbfb8aa3b, v32
	v_mul_f32_e32 v33, 0xbfb8aa3b, v33
	v_exp_f32_e32 v32, v32
	v_exp_f32_e32 v33, v33
	v_sub_f32_e32 v38, 1.0, v84
	v_sub_f32_e32 v39, 1.0, v85
	v_add_f32_e32 v32, 1.0, v32
	v_add_f32_e32 v33, 1.0, v33
	v_rcp_f32_e32 v32, v32
	v_rcp_f32_e32 v33, v33
	v_log_f32_e32 v38, v38
	v_log_f32_e32 v39, v39
	v_pk_add_f32 v[102:103], v[104:105], v[36:37]
	v_pk_add_f32 v[32:33], v[32:33], 1.0 op_sel_hi:[1,0] neg_lo:[1,0] neg_hi:[1,0]
	v_pk_add_f32 v[100:101], v[102:103], v[38:39]
	v_pk_mul_f32 v[82:83], v[56:57], v[32:33]
	v_lshlrev_b32_e32 v32, 16, v125
	v_and_b32_e32 v33, 0xffff0000, v125
	v_mul_f32_e32 v32, 0xbfb8aa3b, v32
	v_mul_f32_e32 v33, 0xbfb8aa3b, v33
	v_exp_f32_e32 v32, v32
	v_exp_f32_e32 v33, v33
	v_sub_f32_e32 v40, 1.0, v82
	v_sub_f32_e32 v41, 1.0, v83
	v_add_f32_e32 v32, 1.0, v32
	v_add_f32_e32 v33, 1.0, v33
	v_rcp_f32_e32 v32, v32
	v_rcp_f32_e32 v33, v33
	v_log_f32_e32 v40, v40
	v_log_f32_e32 v41, v41
	v_pk_add_f32 v[32:33], v[32:33], 1.0 op_sel_hi:[1,0] neg_lo:[1,0] neg_hi:[1,0]
	s_nop 0
	v_pk_mul_f32 v[80:81], v[56:57], v[32:33]
	v_lshlrev_b32_e32 v32, 16, v133
	v_and_b32_e32 v33, 0xffff0000, v133
	v_mul_f32_e32 v32, 0xbfb8aa3b, v32
	v_mul_f32_e32 v33, 0xbfb8aa3b, v33
	v_exp_f32_e32 v32, v32
	v_exp_f32_e32 v33, v33
	v_sub_f32_e32 v42, 1.0, v80
	v_sub_f32_e32 v43, 1.0, v81
	v_add_f32_e32 v32, 1.0, v32
	v_add_f32_e32 v33, 1.0, v33
	v_rcp_f32_e32 v32, v32
	v_rcp_f32_e32 v33, v33
	v_log_f32_e32 v42, v42
	v_log_f32_e32 v43, v43
	v_pk_add_f32 v[98:99], v[100:101], v[40:41]
	v_pk_add_f32 v[32:33], v[32:33], 1.0 op_sel_hi:[1,0] neg_lo:[1,0] neg_hi:[1,0]
	v_pk_add_f32 v[96:97], v[98:99], v[42:43]
	v_pk_mul_f32 v[78:79], v[56:57], v[32:33]
	v_lshlrev_b32_e32 v32, 16, v135
	v_and_b32_e32 v33, 0xffff0000, v135
	v_mul_f32_e32 v32, 0xbfb8aa3b, v32
	v_mul_f32_e32 v33, 0xbfb8aa3b, v33
	v_exp_f32_e32 v32, v32
	v_exp_f32_e32 v33, v33
	v_sub_f32_e32 v44, 1.0, v78
	v_sub_f32_e32 v45, 1.0, v79
	v_add_f32_e32 v32, 1.0, v32
	v_add_f32_e32 v33, 1.0, v33
	v_rcp_f32_e32 v32, v32
	v_rcp_f32_e32 v33, v33
	v_log_f32_e32 v44, v44
	v_log_f32_e32 v45, v45
	v_pk_add_f32 v[32:33], v[32:33], 1.0 op_sel_hi:[1,0] neg_lo:[1,0] neg_hi:[1,0]
	s_nop 0
	v_pk_mul_f32 v[76:77], v[56:57], v[32:33]
	v_lshlrev_b32_e32 v32, 16, v138
	v_and_b32_e32 v33, 0xffff0000, v138
	v_mul_f32_e32 v32, 0xbfb8aa3b, v32
	v_mul_f32_e32 v33, 0xbfb8aa3b, v33
	v_exp_f32_e32 v32, v32
	v_exp_f32_e32 v33, v33
	v_sub_f32_e32 v46, 1.0, v76
	v_sub_f32_e32 v47, 1.0, v77
	v_add_f32_e32 v32, 1.0, v32
	v_add_f32_e32 v33, 1.0, v33
	v_rcp_f32_e32 v32, v32
	v_rcp_f32_e32 v33, v33
	v_log_f32_e32 v46, v46
	v_log_f32_e32 v47, v47
	v_pk_add_f32 v[94:95], v[96:97], v[44:45]
	v_pk_add_f32 v[32:33], v[32:33], 1.0 op_sel_hi:[1,0] neg_lo:[1,0] neg_hi:[1,0]
	v_pk_add_f32 v[92:93], v[94:95], v[46:47]
	v_pk_mul_f32 v[74:75], v[56:57], v[32:33]
	s_nop 0
	v_sub_f32_e32 v32, 1.0, v74
	v_sub_f32_e32 v33, 1.0, v75
	v_log_f32_e32 v32, v32
	v_log_f32_e32 v33, v33
	s_nop 0
	v_pk_add_f32 v[88:89], v[92:93], v[32:33]
	ds_write_b64 v114, v[88:89]
	s_cbranch_scc1 .LBB0_601
	v_lshl_add_u64 v[32:33], v[60:61], 0, s[46:47]
	s_mov_b64 s[2:3], 0x101000
	s_mov_b64 s[52:53], 0x1000
	s_mov_b64 vcc, 0x3000
	v_lshl_add_u64 v[34:35], v[32:33], 0, s[2:3]
	global_load_dword v134, v[34:35], off offset:-4096
	global_load_dword v111, v[34:35], off
	v_lshl_add_u64 v[34:35], v[34:35], 0, s[52:53]
	global_load_dword v136, v[34:35], off
	v_lshl_add_u64 v[34:35], v[34:35], 0, vcc
	global_load_dword v137, v[34:35], off offset:-4096
	global_load_dword v112, v[34:35], off
	v_lshl_add_u64 v[34:35], v[34:35], 0, s[52:53]
	global_load_dword v139, v[34:35], off
	v_lshl_add_u64 v[34:35], v[34:35], 0, vcc
	global_load_dword v140, v[34:35], off offset:-4096
	global_load_dword v115, v[34:35], off
	v_lshl_add_u64 v[34:35], v[34:35], 0, s[52:53]
	global_load_dword v141, v[34:35], off
	v_lshl_add_u64 v[34:35], v[34:35], 0, vcc
	global_load_dword v142, v[34:35], off offset:-4096
	global_load_dword v119, v[34:35], off
	v_lshl_add_u64 v[34:35], v[34:35], 0, s[52:53]
	global_load_dword v143, v[34:35], off
	v_lshl_add_u64 v[34:35], v[34:35], 0, vcc
	global_load_dword v144, v[34:35], off offset:-4096
	global_load_dword v125, v[34:35], off
	v_lshl_add_u64 v[34:35], v[34:35], 0, s[52:53]
	global_load_dword v145, v[34:35], off
	v_lshl_add_u64 v[34:35], v[34:35], 0, vcc
	global_load_dword v146, v[34:35], off offset:-4096
	global_load_dword v133, v[34:35], off
	v_lshl_add_u64 v[34:35], v[34:35], 0, s[52:53]
	global_load_dword v147, v[34:35], off
	v_lshl_add_u64 v[34:35], v[34:35], 0, vcc
	global_load_dword v148, v[34:35], off offset:-4096
	global_load_dword v135, v[34:35], off
	v_lshl_add_u64 v[34:35], v[34:35], 0, s[52:53]
	global_load_dword v149, v[34:35], off
	v_lshl_add_u64 v[34:35], v[34:35], 0, vcc
	global_load_dword v150, v[34:35], off offset:-4096
	global_load_dword v138, v[34:35], off
	v_lshl_add_u64 v[34:35], v[34:35], 0, s[52:53]
	global_load_dword v151, v[34:35], off
